# NSA gates: the three per-query gate values loaded together at unit start (two blocking loads per unit removed)
# speedup vs baseline: 1.0024x; 1.0024x over previous
; __device__ __forceinline__ int mk_ltid() { int t = threadIdx.x; asm volatile("" : "+v"(t)); return t; }
; #define LAS __attribute__((address_space(3)))
; #define NSA_GATE(i) (1.f / (1.f + __expf(-bf2f(QKV[(size_t)(b * SEQ + qpos) * EVEN_PAD + E_GT + hq * 3 + (i)]))))
; __device__ __forceinline__ void nsa_phase(LAS unsigned char* lds, const bf16_t* QKV, const float* relb, const bf16_t* KCMP, const bf16_t* VCMP, bf16_t* AO, float* SCRG, unsigned* CTR, const float* sinks) {
;     ...
;         l += __shfl_xor(l, 32);
;         {
;             const int tid = mk_ltid(), lane = tid & 63, r32 = lane & 31, hi = lane >> 5, qpos = q0 + r32; const LAS float* tb = TS + w * NSA_TS + 64;
;             const float mu = (m == -INFINITY) ? 0.f : m, il = (l > 0.f) ? 1.f / l : 0.f;
;             const float gt0 = NSA_GATE(0);
; #pragma unroll
;             for (int r = 0; r < 16; ++r) { oT[0][r] = 0.f; oT[1][r] = 0.f; }
;             __syncthreads();
;             v4u kr = ld_tile(Kc, 0, 64, tid), vr = ld_tile(Vc, 0, 64, tid);
;             for (int t = 0; t < nct; ++t) {
;                 const int buf = t & 1;
;                 st_k(KT + buf * KTB, kr, tid); st_v(VT + buf * VTB, vr, tid);
;                 __syncthreads();
;                 if (t + 1 < nct) { kr = ld_tile(Kc, 64 * (t + 1), 64, tid); vr = ld_tile(Vc, 64 * (t + 1), 64, tid); }
.LBB0_497:
	v_mov_b32_e32 v74, v202
	s_mul_i32 s18, s18, 3
	v_and_b32_e32 v10, 31, v74
	v_or_b32_e32 v0, s45, v10
	v_add_u32_e32 v0, s43, v0
	v_mov_b64_e32 v[4:5], s[6:7]
	s_ashr_i32 s19, s18, 31
	v_mad_u64_u32 v[4:5], s[26:27], v0, s60, v[4:5]
	v_lshl_add_u64 v[4:5], s[18:19], 1, v[4:5]
	s_movk_i32 s21, 0x1000
	v_add_co_u32_e32 v4, vcc, s21, v4
	v_xor_b32_e32 v0, 32, v236
	s_nop 0
	v_addc_co_u32_e32 v5, vcc, 0, v5, vcc
	global_load_ushort v11, v[4:5], off offset:2560
	global_load_ushort v205, v[4:5], off offset:2562
	global_load_ushort v206, v[4:5], off offset:2564
	v_and_b32_e32 v4, 64, v236
	v_add_u32_e32 v4, 64, v4
	s_lshl_b32 s23, s23, 1
	v_cmp_lt_i32_e32 vcc, v0, v4
	v_ashrrev_i32_e32 v4, 3, v74
	s_add_u32 s26, s30, s23
	v_cndmask_b32_e32 v0, v236, v0, vcc
	v_lshlrev_b32_e32 v6, 3, v74
	v_lshlrev_b32_e32 v7, 4, v74
	v_bfe_i32 v8, v74, 2, 1
	v_lshrrev_b32_e32 v9, 3, v74
	v_bfe_u32 v12, v74, 2, 2
	v_ashrrev_i32_e32 v5, 31, v4
	v_lshlrev_b32_e32 v194, 2, v0
	s_addc_u32 s27, s31, 0
	v_and_b32_e32 v0, 0x70, v7
	v_and_b32_e32 v100, 0x1040, v8
	v_and_b32_e32 v101, 0xffffffc0, v6
	v_and_b32_e32 v102, 48, v7
	v_and_or_b32 v8, v9, 4, v12
	v_lshlrev_b64 v[6:7], 7, v[4:5]
	v_lshlrev_b32_e32 v105, 6, v8
	v_lshl_add_u64 v[8:9], s[4:5], 0, v[6:7]
	v_lshl_add_u64 v[6:7], s[26:27], 0, v[6:7]
	v_lshl_add_u64 v[8:9], v[8:9], 0, v[0:1]
	v_lshl_add_u64 v[6:7], v[6:7], 0, v[0:1]
	s_barrier
	global_load_dwordx4 v[66:69], v[8:9], off
	global_load_dwordx4 v[70:73], v[6:7], off
	ds_bpermute_b32 v12, v194, v3
	v_lshl_add_u64 v[76:77], s[4:5], 0, v[0:1]
	v_and_b32_e32 v13, 16, v74
	v_bfe_u32 v98, v74, 5, 1
	v_mul_i32_i24_e32 v14, 0xffffffc0, v98
	s_waitcnt lgkmcnt(0)
	v_add_f32_e32 v3, v3, v12
	v_div_scale_f32 v5, s[4:5], v3, v3, 1.0
	v_rcp_f32_e32 v8, v5
	v_div_scale_f32 v6, vcc, 1.0, v3, 1.0
	v_mov_b32_e32 v2, 0
	v_fma_f32 v7, -v5, v8, 1.0
	v_fmac_f32_e32 v8, v7, v8
	v_mul_f32_e32 v7, v6, v8
	v_fma_f32 v9, -v5, v7, v6
	v_fmac_f32_e32 v7, v9, v8
	v_fma_f32 v5, -v5, v7, v6
	v_div_fmas_f32 v5, v5, v8, v7
	v_div_fixup_f32 v5, v5, v3, 1.0
	v_cmp_lt_f32_e32 vcc, 0, v3
	s_mov_b32 s21, 0
	v_mul_lo_u32 v99, v4, s67
	v_cndmask_b32_e32 v80, 0, v5, vcc
	v_mul_u32_u24_e32 v103, 0x90, v10
	v_lshlrev_b32_e32 v104, 4, v98
	v_lshl_add_u64 v[78:79], s[26:27], 0, v[0:1]
	v_mov_b32_e32 v81, v80
	v_add_u32_e32 v109, 64, v4
	s_mov_b32 s23, 0
	v_mov_b32_e32 v4, v2
	v_mov_b32_e32 v12, v2
	v_mov_b32_e32 v15, v2
	v_mov_b32_e32 v16, v2
	v_mov_b32_e32 v17, v2
	v_mov_b32_e32 v18, v2
	v_mov_b32_e32 v19, v2
	v_mov_b32_e32 v20, v2
	v_mov_b32_e32 v21, v2
	v_mov_b32_e32 v22, v2
	v_mov_b32_e32 v23, v2
	v_mov_b32_e32 v24, v2
	v_mov_b32_e32 v25, v2
	v_mov_b32_e32 v26, v2
	v_mov_b32_e32 v27, v2
	v_mov_b32_e32 v28, v2
	v_mov_b32_e32 v29, v2
	v_mov_b32_e32 v30, v2
	s_waitcnt vmcnt(2)
	v_lshlrev_b32_e32 v6, 16, v11
	v_mul_f32_e32 v6, 0xbfb8aa3b, v6
	v_exp_f32_e32 v6, v6
	v_mov_b32_e32 v11, v2
	v_mov_b32_e32 v31, v2
	v_mov_b32_e32 v32, v2
	v_add_f32_e32 v6, 1.0, v6
	v_div_scale_f32 v7, s[4:5], v6, v6, 1.0
	v_rcp_f32_e32 v8, v7
	v_div_scale_f32 v3, vcc, 1.0, v6, 1.0
	v_mov_b32_e32 v33, v2
	v_fma_f32 v5, -v7, v8, 1.0
	v_fmac_f32_e32 v8, v5, v8
	v_mul_f32_e32 v5, v3, v8
	v_fma_f32 v9, -v7, v5, v3
	v_fmac_f32_e32 v5, v9, v8
	v_fma_f32 v3, -v7, v5, v3
	v_div_fmas_f32 v3, v3, v8, v5
	v_div_fixup_f32 v82, v3, v6, 1.0
	v_lshlrev_b32_e32 v3, 2, v74
	v_and_or_b32 v3, v3, 12, v13
	v_lshlrev_b32_e32 v106, 1, v3
	v_lshlrev_b32_e32 v3, 2, v98
	v_lshl_or_b32 v3, v10, 8, v3
	v_add_u32_e32 v107, 0, v3
	v_or_b32_e32 v3, v14, v10
	v_subrev_u32_e32 v3, s22, v3
	v_mov_b32_e32 v83, v82
	v_mov_b32_e32 v84, v82
	v_mov_b32_e32 v85, v82
	v_mov_b32_e32 v86, v82
	v_mov_b32_e32 v87, v82
	v_mov_b32_e32 v88, v82
	v_mov_b32_e32 v89, v82
	v_mov_b32_e32 v90, v82
	v_mov_b32_e32 v91, v82
	v_mov_b32_e32 v92, v82
	v_mov_b32_e32 v93, v82
	v_mov_b32_e32 v94, v82
	v_mov_b32_e32 v95, v82
	v_mov_b32_e32 v96, v82
	v_mov_b32_e32 v97, v82
	v_add_u32_e32 v108, 0xe30, v3
	v_mov_b32_e32 v3, v2
	v_mov_b32_e32 v5, v2
	v_mov_b32_e32 v6, v2
	v_mov_b32_e32 v7, v2
	v_mov_b32_e32 v8, v2
	v_mov_b32_e32 v9, v2
	v_mov_b32_e32 v10, v2
	v_mov_b32_e32 v13, v2
	v_mov_b32_e32 v14, v2
	s_branch .LBB0_499

; #define NSA_GATE(i) (1.f / (1.f + __expf(-bf2f(QKV[(size_t)(b * SEQ + qpos) * EVEN_PAD + E_GT + hq * 3 + (i)]))))
; __device__ __forceinline__ void nsa_phase(LAS unsigned char* lds, const bf16_t* QKV, const float* relb, const bf16_t* KCMP, const bf16_t* VCMP, bf16_t* AO, float* SCRG, unsigned* CTR, const float* sinks) {
;     ...
;             l += __shfl_xor(l, 32);
;             const float scl = (l > 0.f) ? NSA_GATE(1) / l : 0.f;
.LBB0_560:
	ds_bpermute_b32 v0, v194, v216
	s_waitcnt lgkmcnt(0)
	v_add_f32_e32 v34, v216, v0
	v_mov_b32_e32 v0, 0
	v_cmp_lt_f32_e32 vcc, 0, v34
	s_and_saveexec_b64 s[0:1], vcc
	s_cbranch_execz .LBB0_562
	v_add_u32_e32 v0, s43, v187
	v_mov_b64_e32 v[36:37], s[6:7]
	v_mad_u64_u32 v[36:37], s[4:5], v0, s60, v[36:37]
	v_lshl_add_u64 v[36:37], s[18:19], 1, v[36:37]
	v_add_co_u32_e32 v36, vcc, 0x1000, v36
	s_nop 1
	v_addc_co_u32_e32 v37, vcc, 0, v37, vcc
	v_mov_b32_e32 v0, v205
	s_waitcnt vmcnt(0)
	v_lshlrev_b32_e32 v0, 16, v0
	v_mul_f32_e32 v0, 0xbfb8aa3b, v0
	v_exp_f32_e32 v0, v0
	s_nop 0
	v_add_f32_e32 v0, 1.0, v0
	v_div_scale_f32 v35, s[4:5], v0, v0, 1.0
	v_rcp_f32_e32 v36, v35
	v_div_scale_f32 v37, vcc, 1.0, v0, 1.0
	v_fma_f32 v38, -v35, v36, 1.0
	v_fmac_f32_e32 v36, v38, v36
	v_mul_f32_e32 v38, v37, v36
	v_fma_f32 v39, -v35, v38, v37
	v_fmac_f32_e32 v38, v39, v36
	v_fma_f32 v35, -v35, v38, v37
	v_div_fmas_f32 v35, v35, v36, v38
	v_div_fixup_f32 v0, v35, v0, 1.0
	v_div_scale_f32 v35, s[4:5], v34, v34, v0
	v_rcp_f32_e32 v36, v35
	v_div_scale_f32 v37, vcc, v0, v34, v0
	v_fma_f32 v38, -v35, v36, 1.0
	v_fmac_f32_e32 v36, v38, v36
	v_mul_f32_e32 v38, v37, v36
	v_fma_f32 v39, -v35, v38, v37
	v_fmac_f32_e32 v38, v39, v36
	v_fma_f32 v35, -v35, v38, v37
	v_div_fmas_f32 v35, v35, v36, v38
	v_div_fixup_f32 v0, v35, v34, v0

; #define NSA_GATE(i) (1.f / (1.f + __expf(-bf2f(QKV[(size_t)(b * SEQ + qpos) * EVEN_PAD + E_GT + hq * 3 + (i)]))))
; __device__ __forceinline__ void nsa_phase(LAS unsigned char* lds, const bf16_t* QKV, const float* relb, const bf16_t* KCMP, const bf16_t* VCMP, bf16_t* AO, float* SCRG, unsigned* CTR, const float* sinks) {
;     ...
;             l += __shfl_xor(l, 32);
;             const float scl = (l > 0.f) ? NSA_GATE(2) / l : 0.f;
.LBB0_597:
	ds_bpermute_b32 v0, v194, v200
	v_mov_b32_e32 v34, 0
	s_waitcnt lgkmcnt(0)
	v_add_f32_e32 v35, v200, v0
	v_cmp_lt_f32_e32 vcc, 0, v35
	v_add_u32_e32 v0, s43, v187
	s_and_saveexec_b64 s[0:1], vcc
	s_cbranch_execz .LBB0_468
	v_mov_b64_e32 v[36:37], s[6:7]
	v_mad_u64_u32 v[36:37], s[4:5], v0, s60, v[36:37]
	v_lshl_add_u64 v[36:37], s[18:19], 1, v[36:37]
	v_add_co_u32_e32 v36, vcc, 0x1000, v36
	s_nop 1
	v_addc_co_u32_e32 v37, vcc, 0, v37, vcc
	v_mov_b32_e32 v34, v206
	s_waitcnt vmcnt(0)
	v_lshlrev_b32_e32 v34, 16, v34
	v_mul_f32_e32 v34, 0xbfb8aa3b, v34
	v_exp_f32_e32 v34, v34
	s_nop 0
	v_add_f32_e32 v34, 1.0, v34
	v_div_scale_f32 v36, s[4:5], v34, v34, 1.0
	v_rcp_f32_e32 v37, v36
	v_div_scale_f32 v38, vcc, 1.0, v34, 1.0
	v_fma_f32 v39, -v36, v37, 1.0
	v_fmac_f32_e32 v37, v39, v37
	v_mul_f32_e32 v39, v38, v37
	v_fma_f32 v40, -v36, v39, v38
	v_fmac_f32_e32 v39, v40, v37
	v_fma_f32 v36, -v36, v39, v38
	v_div_fmas_f32 v36, v36, v37, v39
	v_div_fixup_f32 v34, v36, v34, 1.0
	v_div_scale_f32 v36, s[4:5], v35, v35, v34
	v_rcp_f32_e32 v37, v36
	v_div_scale_f32 v38, vcc, v34, v35, v34
	v_fma_f32 v39, -v36, v37, 1.0
	v_fmac_f32_e32 v37, v39, v37
	v_mul_f32_e32 v39, v38, v37
	v_fma_f32 v40, -v36, v39, v38
	v_fmac_f32_e32 v39, v40, v37
	v_fma_f32 v36, -v36, v39, v38
	v_div_fmas_f32 v36, v36, v37, v39
	v_div_fixup_f32 v34, v36, v35, v34
	s_branch .LBB0_468
